# H2 loader waves fetch the intra-chunk partial with two 16-byte loads per lane instead of four 8-byte ones (13 loads and 13 LDS writes per chunk instead of 15)
# baseline (speedup 1.0000x reference)
; #define H2_PRIV(cc, VT_, OI_) do { const int tok0_ = b * T + 64 * (cc); \
;         const bf16* vp_ = Z2 + (size_t)(tok0_ + (vcol >> 1)) * NH2 + 2048 + h * 128 + (vcol & 1) * 64 + 8 * fq; VT_[0] = *(const u32x4*)vp_; VT_[1] = *(const u32x4*)(vp_ + 32); \
;         _Pragma("unroll") for (int tt_ = 0; tt_ < 4; ++tt_) OI_[tt_] = OI[((size_t)((unit0 + (cc)) * 4 + tt_) * 8 + w) * 64 + lane]; } while (0)
; template <bool DRY> DI void hgrn2_phase(LAS unsigned char* L, bf16* Z2, const float* DEC, unsigned long long* OIW, int bh2, int tid) {
;     ...
;     u32x4 vtf[2] = {(u32x4){0u, 0u, 0u, 0u}, (u32x4){0u, 0u, 0u, 0u}}; unsigned long long oi[4] = {0ull, 0ull, 0ull, 0ull};
;     u32x4 nvt[2] = {(u32x4){0u, 0u, 0u, 0u}, (u32x4){0u, 0u, 0u, 0u}}; unsigned long long noi[4] = {0ull, 0ull, 0ull, 0ull};
;     H2_LOAD(0, sqA, skA, sdA); H2_WRITE(0, sqA, skA, sdA); if (cw) H2_PRIV(0, vtf, oi);
;     H2_LOAD(1, sqA, skA, sdA); if (cw) H2_PRIV(1, nvt, noi);
.Lh2_loader:
	s_sub_u32 s51, s50, 4
	s_cmp_eq_u32 s51, 0
	s_cselect_b32 s65, 1, 0
	v_and_b32_e32 v236, 15, v130
	v_lshrrev_b32_e32 v237, 4, v130
	s_lshl_b32 s42, s51, 2
	v_add_u32_e32 v245, s42, v237
	v_lshlrev_b32_e32 v246, 13, v245
	v_lshl_add_u32 v190, v236, 4, v246
	v_add_u32_e32 v191, 0x20000, v190
	v_add_u32_e32 v192, 0x40000, v190
	v_add_u32_e32 v193, 0x60000, v190
	v_lshlrev_b32_e32 v194, 4, v130
	s_lshl_b32 s43, s39, 2
	s_add_u32 s43, s43, s51
	s_lshl_b32 s42, s43, 4
	v_add_u32_e32 v246, s42, v236
	v_lshrrev_b32_e32 v247, 1, v246
	v_lshlrev_b32_e32 v247, 13, v247
	v_and_b32_e32 v246, 1, v246
	v_lshl_add_u32 v247, v246, 7, v247
	v_lshl_add_u32 v247, v237, 4, v247
	v_add_u32_e32 v195, 0x1000, v247
	s_lshl_b32 s42, s43, 9
	v_and_b32_e32 v246, 31, v130
	v_lshlrev_b32_e32 v246, 4, v246
	v_lshrrev_b32_e32 v247, 5, v130
	v_lshl_add_u32 v246, v247, 12, v246
	v_add_u32_e32 v198, s42, v246
	v_add_u32_e32 v199, 0x2000, v198
	v_mul_u32_u24_e32 v246, 0x110, v245
	v_lshl_add_u32 v200, v236, 4, v246
	v_lshrrev_b32_e32 v246, 3, v236
	v_lshl_add_u32 v246, v245, 1, v246
	v_mul_u32_u24_e32 v246, 0x90, v246
	v_and_b32_e32 v247, 7, v236
	v_lshl_add_u32 v201, v247, 4, v246
	v_lshlrev_b32_e32 v206, 4, v130
	s_lshl_b32 s42, s51, 11
	v_lshlrev_b32_e32 v246, 4, v130
	v_add_u32_e32 v207, s42, v246
	v_and_b32_e32 v246, 31, v130
	v_lshlrev_b32_e32 v246, 4, v246
	v_lshrrev_b32_e32 v247, 5, v130
	v_lshl_add_u32 v246, v247, 9, v246
	v_add_u32_e32 v208, s42, v246
	v_add_u32_e32 v209, 0xce00, v200
	v_add_u32_e32 v232, 0xce00, v201
	v_add_u32_e32 v233, 0xce00, v206
	v_add_u32_e32 v234, 0xce00, v207
	v_add_u32_e32 v235, 0xce00, v208
	s_mov_b32 s56, 0
	s_lshl_b32 s57, s56, 19
	s_add_u32 s58, s44, s57
	s_addc_u32 s59, s45, 0
	s_lshl_b32 s57, s56, 9
	s_add_u32 s60, s46, s57
	s_addc_u32 s61, s47, 0
	s_lshl_b32 s57, s56, 14
	s_add_u32 s62, s48, s57
	s_addc_u32 s63, s49, 0
	global_load_dwordx4 v[2:5], v190, s[58:59]
	global_load_dwordx4 v[18:21], v190, s[58:59] offset:2048
	global_load_dwordx4 v[6:9], v191, s[58:59]
	global_load_dwordx4 v[22:25], v191, s[58:59] offset:2048
	global_load_dwordx4 v[10:13], v192, s[58:59]
	global_load_dwordx4 v[26:29], v192, s[58:59] offset:2048
	global_load_dwordx4 v[14:17], v193, s[58:59]
	global_load_dwordx4 v[30:33], v193, s[58:59] offset:2048
	global_load_dwordx4 v[34:37], v194, s[60:61]
	global_load_dwordx4 v[38:41], v195, s[58:59]
	global_load_dwordx4 v[42:45], v195, s[58:59] offset:64
	global_load_dwordx4 v[46:49], v198, s[62:63]
	global_load_dwordx4 v[50:53], v199, s[62:63]
	s_mov_b32 s56, 1
	s_lshl_b32 s57, s56, 19
	s_add_u32 s58, s44, s57
	s_addc_u32 s59, s45, 0
	s_lshl_b32 s57, s56, 9
	s_add_u32 s60, s46, s57
	s_addc_u32 s61, s47, 0
	s_lshl_b32 s57, s56, 14
	s_add_u32 s62, s48, s57
	s_addc_u32 s63, s49, 0
	global_load_dwordx4 v[54:57], v190, s[58:59]
	global_load_dwordx4 v[70:73], v190, s[58:59] offset:2048
	global_load_dwordx4 v[58:61], v191, s[58:59]
	global_load_dwordx4 v[74:77], v191, s[58:59] offset:2048
	global_load_dwordx4 v[62:65], v192, s[58:59]
	global_load_dwordx4 v[78:81], v192, s[58:59] offset:2048
	global_load_dwordx4 v[66:69], v193, s[58:59]
	global_load_dwordx4 v[82:85], v193, s[58:59] offset:2048
	global_load_dwordx4 v[86:89], v194, s[60:61]
	global_load_dwordx4 v[90:93], v195, s[58:59]
	global_load_dwordx4 v[94:97], v195, s[58:59] offset:64
	global_load_dwordx4 v[98:101], v198, s[62:63]
	global_load_dwordx4 v[102:105], v199, s[62:63]
	s_mov_b32 s56, 2
	s_lshl_b32 s57, s56, 19
	s_add_u32 s58, s44, s57
	s_addc_u32 s59, s45, 0
	s_lshl_b32 s57, s56, 9
	s_add_u32 s60, s46, s57
	s_addc_u32 s61, s47, 0
	s_lshl_b32 s57, s56, 14
	s_add_u32 s62, s48, s57
	s_addc_u32 s63, s49, 0
	global_load_dwordx4 v[106:109], v190, s[58:59]
	global_load_dwordx4 v[122:125], v190, s[58:59] offset:2048
	global_load_dwordx4 v[110:113], v191, s[58:59]
	global_load_dwordx4 v[126:129], v191, s[58:59] offset:2048
	global_load_dwordx4 v[114:117], v192, s[58:59]
	global_load_dwordx4 v[130:133], v192, s[58:59] offset:2048
	global_load_dwordx4 v[118:121], v193, s[58:59]
	global_load_dwordx4 v[134:137], v193, s[58:59] offset:2048
	global_load_dwordx4 v[138:141], v194, s[60:61]
	global_load_dwordx4 v[142:145], v195, s[58:59]
	global_load_dwordx4 v[146:149], v195, s[58:59] offset:64
	global_load_dwordx4 v[150:153], v198, s[62:63]
	global_load_dwordx4 v[154:157], v199, s[62:63]
	s_mov_b32 s56, 3
	s_lshl_b32 s57, s56, 19
	s_add_u32 s58, s44, s57
	s_addc_u32 s59, s45, 0
	s_lshl_b32 s57, s56, 9
	s_add_u32 s60, s46, s57
	s_addc_u32 s61, s47, 0
	s_lshl_b32 s57, s56, 14
	s_add_u32 s62, s48, s57
	s_addc_u32 s63, s49, 0
	global_load_dwordx4 v[158:161], v190, s[58:59]
	global_load_dwordx4 v[174:177], v190, s[58:59] offset:2048
	global_load_dwordx4 v[162:165], v191, s[58:59]
	global_load_dwordx4 v[178:181], v191, s[58:59] offset:2048
	global_load_dwordx4 v[166:169], v192, s[58:59]
	global_load_dwordx4 v[182:185], v192, s[58:59] offset:2048
	global_load_dwordx4 v[170:173], v193, s[58:59]
	global_load_dwordx4 v[186:189], v193, s[58:59] offset:2048
	global_load_dwordx4 v[212:215], v194, s[60:61]
	global_load_dwordx4 v[216:219], v195, s[58:59]
	global_load_dwordx4 v[220:223], v195, s[58:59] offset:64
	global_load_dwordx4 v[224:227], v198, s[62:63]
	global_load_dwordx4 v[228:231], v199, s[62:63]
	s_waitcnt vmcnt(39)
	ds_write_b128 v200, v[2:5] offset:0
	ds_write_b128 v201, v[18:21] offset:17408
	ds_write_b128 v200, v[6:9] offset:4352
	ds_write_b128 v201, v[22:25] offset:22016
	ds_write_b128 v200, v[10:13] offset:8704
	ds_write_b128 v201, v[26:29] offset:26624
	ds_write_b128 v200, v[14:17] offset:13056
	ds_write_b128 v201, v[30:33] offset:31232
	ds_write_b128 v207, v[38:41] offset:36352
	ds_write_b128 v207, v[42:45] offset:37376
	ds_write_b128 v208, v[46:49] offset:44544
	ds_write_b128 v208, v[50:53] offset:45568
	s_cmp_eq_u32 s65, 0
	s_cbranch_scc1 .Lh2l_nodec_p
	s_mov_b32 exec_hi, 0
	ds_write_b128 v206, v[34:37] offset:35840
	s_mov_b32 exec_hi, -1
; #define LAS __attribute__((address_space(3)))
; #define LBAR() do { asm volatile("s_waitcnt lgkmcnt(0)" ::: "memory"); __builtin_amdgcn_s_barrier(); asm volatile("" ::: "memory"); } while (0)
; #define H2_PRIV(cc, VT_, OI_) do { const int tok0_ = b * T + 64 * (cc); \
;         const bf16* vp_ = Z2 + (size_t)(tok0_ + (vcol >> 1)) * NH2 + 2048 + h * 128 + (vcol & 1) * 64 + 8 * fq; VT_[0] = *(const u32x4*)vp_; VT_[1] = *(const u32x4*)(vp_ + 32); \
;         _Pragma("unroll") for (int tt_ = 0; tt_ < 4; ++tt_) OI_[tt_] = OI[((size_t)((unit0 + (cc)) * 4 + tt_) * 8 + w) * 64 + lane]; } while (0)
; template <bool DRY> DI void hgrn2_phase(LAS unsigned char* L, bf16* Z2, const float* DEC, unsigned long long* OIW, int bh2, int tid) {
;     ...
;     H2_LOAD(0, sqA, skA, sdA); H2_WRITE(0, sqA, skA, sdA); if (cw) H2_PRIV(0, vtf, oi);
;     H2_LOAD(1, sqA, skA, sdA); if (cw) H2_PRIV(1, nvt, noi);
;     f32x4 S[8];
; #pragma unroll
;     for (int nt = 0; nt < 8; ++nt) S[nt] = (f32x4){0.f, 0.f, 0.f, 0.f};
;     __syncthreads();
;     for (int c = 0; c < 64; ++c) {
;         LAS unsigned char* Bc = L + (c & 1) * H2_BUF;
;         asm volatile("" : "+v"(vtf[0]), "+v"(vtf[1]), "+v"(oi[0]), "+v"(oi[1]), "+v"(oi[2]), "+v"(oi[3]), "+v"(nvt[0]), "+v"(nvt[1]), "+v"(noi[0]), "+v"(noi[1]), "+v"(noi[2]), "+v"(noi[3]));
;         asm volatile("" : "+v"(sqA[0]), "+v"(sqA[1]), "+v"(skA[0]), "+v"(skA[1]), "+v"(sdA));
;         u32x4 sqB[2], skB[2]; f32x4 sdB = (f32x4){0.f, 0.f, 0.f, 0.f}; u32x4 nnvt[2] = {(u32x4){0u, 0u, 0u, 0u}, (u32x4){0u, 0u, 0u, 0u}}; unsigned long long nnoi[4] = {0ull, 0ull, 0ull, 0ull};
;         const int c2 = c + 2 < 64 ? c + 2 : 63;
;         H2_LOAD(c2, sqB, skB, sdB); if (cw) H2_PRIV(c2, nnvt, nnoi);
;     ...
;         if (c + 1 < 64) H2_WRITE((c + 1) & 1, sqA, skA, sdA);
;         vtf[0] = nvt[0]; vtf[1] = nvt[1]; nvt[0] = nnvt[0]; nvt[1] = nnvt[1];
; #pragma unroll
;         for (int i = 0; i < 4; ++i) { oi[i] = noi[i]; noi[i] = nnoi[i]; }
;         sqA[0] = sqB[0]; sqA[1] = sqB[1]; skA[0] = skB[0]; skA[1] = skB[1]; sdA = sdB;
;         LBAR();
.Lh2l_nodec_p:
	s_mov_b32 s56, 4
	s_lshl_b32 s57, s56, 19
	s_add_u32 s58, s44, s57
	s_addc_u32 s59, s45, 0
	s_lshl_b32 s57, s56, 9
	s_add_u32 s60, s46, s57
	s_addc_u32 s61, s47, 0
	s_lshl_b32 s57, s56, 14
	s_add_u32 s62, s48, s57
	s_addc_u32 s63, s49, 0
	global_load_dwordx4 v[2:5], v190, s[58:59]
	global_load_dwordx4 v[18:21], v190, s[58:59] offset:2048
	global_load_dwordx4 v[6:9], v191, s[58:59]
	global_load_dwordx4 v[22:25], v191, s[58:59] offset:2048
	global_load_dwordx4 v[10:13], v192, s[58:59]
	global_load_dwordx4 v[26:29], v192, s[58:59] offset:2048
	global_load_dwordx4 v[14:17], v193, s[58:59]
	global_load_dwordx4 v[30:33], v193, s[58:59] offset:2048
	global_load_dwordx4 v[34:37], v194, s[60:61]
	global_load_dwordx4 v[38:41], v195, s[58:59]
	global_load_dwordx4 v[42:45], v195, s[58:59] offset:64
	global_load_dwordx4 v[46:49], v198, s[62:63]
	global_load_dwordx4 v[50:53], v199, s[62:63]
	s_mov_b32 s64, 0
	s_waitcnt lgkmcnt(0)
	s_barrier
.Lh2l_loop:
	s_waitcnt vmcnt(39)
	ds_write_b128 v209, v[54:57] offset:0
	ds_write_b128 v232, v[70:73] offset:17408
	ds_write_b128 v209, v[58:61] offset:4352
	ds_write_b128 v232, v[74:77] offset:22016
	ds_write_b128 v209, v[62:65] offset:8704
	ds_write_b128 v232, v[78:81] offset:26624
	ds_write_b128 v209, v[66:69] offset:13056
	ds_write_b128 v232, v[82:85] offset:31232
	ds_write_b128 v234, v[90:93] offset:36352
	ds_write_b128 v234, v[94:97] offset:37376
	ds_write_b128 v235, v[98:101] offset:44544
	ds_write_b128 v235, v[102:105] offset:45568
	s_cmp_eq_u32 s65, 0
	s_cbranch_scc1 .Lh2l_nodec_u0
	s_mov_b32 exec_hi, 0
	ds_write_b128 v233, v[86:89] offset:35840
	s_mov_b32 exec_hi, -1
.Lh2l_nodec_u0:
	s_add_u32 s56, s64, 5
	s_min_u32 s56, s56, 63
	s_lshl_b32 s57, s56, 19
	s_add_u32 s58, s44, s57
	s_addc_u32 s59, s45, 0
	s_lshl_b32 s57, s56, 9
	s_add_u32 s60, s46, s57
	s_addc_u32 s61, s47, 0
	s_lshl_b32 s57, s56, 14
	s_add_u32 s62, s48, s57
	s_addc_u32 s63, s49, 0
	global_load_dwordx4 v[54:57], v190, s[58:59]
	global_load_dwordx4 v[70:73], v190, s[58:59] offset:2048
	global_load_dwordx4 v[58:61], v191, s[58:59]
	global_load_dwordx4 v[74:77], v191, s[58:59] offset:2048
	global_load_dwordx4 v[62:65], v192, s[58:59]
	global_load_dwordx4 v[78:81], v192, s[58:59] offset:2048
	global_load_dwordx4 v[66:69], v193, s[58:59]
	global_load_dwordx4 v[82:85], v193, s[58:59] offset:2048
	global_load_dwordx4 v[86:89], v194, s[60:61]
	global_load_dwordx4 v[90:93], v195, s[58:59]
	global_load_dwordx4 v[94:97], v195, s[58:59] offset:64
	global_load_dwordx4 v[98:101], v198, s[62:63]
	global_load_dwordx4 v[102:105], v199, s[62:63]
	s_waitcnt lgkmcnt(0)
	s_barrier
	s_waitcnt vmcnt(39)
	ds_write_b128 v200, v[106:109] offset:0
	ds_write_b128 v201, v[122:125] offset:17408
	ds_write_b128 v200, v[110:113] offset:4352
	ds_write_b128 v201, v[126:129] offset:22016
	ds_write_b128 v200, v[114:117] offset:8704
	ds_write_b128 v201, v[130:133] offset:26624
	ds_write_b128 v200, v[118:121] offset:13056
	ds_write_b128 v201, v[134:137] offset:31232
	ds_write_b128 v207, v[142:145] offset:36352
	ds_write_b128 v207, v[146:149] offset:37376
	ds_write_b128 v208, v[150:153] offset:44544
	ds_write_b128 v208, v[154:157] offset:45568
	s_cmp_eq_u32 s65, 0
	s_cbranch_scc1 .Lh2l_nodec_u1
	s_mov_b32 exec_hi, 0
	ds_write_b128 v206, v[138:141] offset:35840
	s_mov_b32 exec_hi, -1
; #define LAS __attribute__((address_space(3)))
; template <bool DRY> DI void hgrn2_phase(LAS unsigned char* L, bf16* Z2, const float* DEC, unsigned long long* OIW, int bh2, int tid) {
;     ...
;     for (int c = 0; c < 64; ++c) {
;         LAS unsigned char* Bc = L + (c & 1) * H2_BUF;
;         asm volatile("" : "+v"(vtf[0]), "+v"(vtf[1]), "+v"(oi[0]), "+v"(oi[1]), "+v"(oi[2]), "+v"(oi[3]), "+v"(nvt[0]), "+v"(nvt[1]), "+v"(noi[0]), "+v"(noi[1]), "+v"(noi[2]), "+v"(noi[3]));
;         asm volatile("" : "+v"(sqA[0]), "+v"(sqA[1]), "+v"(skA[0]), "+v"(skA[1]), "+v"(sdA));
;         u32x4 sqB[2], skB[2]; f32x4 sdB = (f32x4){0.f, 0.f, 0.f, 0.f}; u32x4 nnvt[2] = {(u32x4){0u, 0u, 0u, 0u}, (u32x4){0u, 0u, 0u, 0u}}; unsigned long long nnoi[4] = {0ull, 0ull, 0ull, 0ull};
;         const int c2 = c + 2 < 64 ? c + 2 : 63;
;         H2_LOAD(c2, sqB, skB, sdB); if (cw) H2_PRIV(c2, nnvt, nnoi);
;         if (cw) {
;         bf16x8 qa[4][4];
; #pragma unroll
;         for (int tt = 0; tt < 4; ++tt)
; #pragma unroll
;             for (int np = 0; np < 4; ++np) { const LAS unsigned char* qp = Bc + (16 * tt + fr) * 272 + (32 * np + 4 * fq) * 2;
;                 const s16x4 lo = *(const LAS s16x4*)qp, hi = *(const LAS s16x4*)(qp + 32); qa[tt][np] = __builtin_shufflevector(lo, hi, 0, 1, 2, 3, 4, 5, 6, 7); }
;         bf16x8 sb[4];
; #pragma unroll
;         for (int np = 0; np < 4; ++np) { u32x4 pw; pw.x = pk2(S[2 * np][0], S[2 * np][1]); pw.y = pk2(S[2 * np][2], S[2 * np][3]); pw.z = pk2(S[2 * np + 1][0], S[2 * np + 1][1]); pw.w = pk2(S[2 * np + 1][2], S[2 * np + 1][3]); sb[np] = mk8(pw); }
;         f32x4 o[4];
; #pragma unroll
;         for (int tt = 0; tt < 4; ++tt) { const unsigned lo = (unsigned)oi[tt], hi = (unsigned)(oi[tt] >> 32); o[tt] = (f32x4){lo16(lo), hi16(lo), lo16(hi), hi16(hi)}; }
; #pragma unroll
;         for (int np = 0; np < 4; ++np)
; #pragma unroll
;             for (int tt = 0; tt < 4; ++tt) o[tt] = MFMA16(sb[np], qa[tt][np], o[tt]);
;         if (!DRY) {
; #pragma unroll
;             for (int tt = 0; tt < 4; ++tt) OIW[((size_t)((unit0 + c) * 4 + tt) * 8 + w) * 64 + lane] = (unsigned long long)pk2(o[tt][0], o[tt][1]) | ((unsigned long long)pk2(o[tt][2], o[tt][3]) << 32);
;         } else { asm volatile("" :: "v"(o[0]), "v"(o[1]), "v"(o[2]), "v"(o[3])); }
;         bf16x8 ka[8][2];
; #pragma unroll
;         for (int nt = 0; nt < 8; ++nt)
; #pragma unroll
.Lh2l_nodec_u1:
	s_add_u32 s56, s64, 6
	s_min_u32 s56, s56, 63
	s_lshl_b32 s57, s56, 19
	s_add_u32 s58, s44, s57
	s_addc_u32 s59, s45, 0
	s_lshl_b32 s57, s56, 9
	s_add_u32 s60, s46, s57
	s_addc_u32 s61, s47, 0
	s_lshl_b32 s57, s56, 14
	s_add_u32 s62, s48, s57
	s_addc_u32 s63, s49, 0
	global_load_dwordx4 v[106:109], v190, s[58:59]
	global_load_dwordx4 v[122:125], v190, s[58:59] offset:2048
	global_load_dwordx4 v[110:113], v191, s[58:59]
	global_load_dwordx4 v[126:129], v191, s[58:59] offset:2048
	global_load_dwordx4 v[114:117], v192, s[58:59]
	global_load_dwordx4 v[130:133], v192, s[58:59] offset:2048
	global_load_dwordx4 v[118:121], v193, s[58:59]
	global_load_dwordx4 v[134:137], v193, s[58:59] offset:2048
	global_load_dwordx4 v[138:141], v194, s[60:61]
	global_load_dwordx4 v[142:145], v195, s[58:59]
	global_load_dwordx4 v[146:149], v195, s[58:59] offset:64
	global_load_dwordx4 v[150:153], v198, s[62:63]
	global_load_dwordx4 v[154:157], v199, s[62:63]
	s_waitcnt lgkmcnt(0)
	s_barrier
	s_waitcnt vmcnt(39)
	ds_write_b128 v209, v[158:161] offset:0
	ds_write_b128 v232, v[174:177] offset:17408
	ds_write_b128 v209, v[162:165] offset:4352
	ds_write_b128 v232, v[178:181] offset:22016
	ds_write_b128 v209, v[166:169] offset:8704
	ds_write_b128 v232, v[182:185] offset:26624
	ds_write_b128 v209, v[170:173] offset:13056
	ds_write_b128 v232, v[186:189] offset:31232
	ds_write_b128 v234, v[216:219] offset:36352
	ds_write_b128 v234, v[220:223] offset:37376
	ds_write_b128 v235, v[224:227] offset:44544
	ds_write_b128 v235, v[228:231] offset:45568
	s_cmp_eq_u32 s65, 0
	s_cbranch_scc1 .Lh2l_nodec_u2
	s_mov_b32 exec_hi, 0
	ds_write_b128 v233, v[212:215] offset:35840
	s_mov_b32 exec_hi, -1
.Lh2l_nodec_u2:
	s_add_u32 s56, s64, 7
	s_min_u32 s56, s56, 63
	s_lshl_b32 s57, s56, 19
	s_add_u32 s58, s44, s57
	s_addc_u32 s59, s45, 0
	s_lshl_b32 s57, s56, 9
	s_add_u32 s60, s46, s57
	s_addc_u32 s61, s47, 0
	s_lshl_b32 s57, s56, 14
	s_add_u32 s62, s48, s57
	s_addc_u32 s63, s49, 0
	global_load_dwordx4 v[158:161], v190, s[58:59]
	global_load_dwordx4 v[174:177], v190, s[58:59] offset:2048
	global_load_dwordx4 v[162:165], v191, s[58:59]
	global_load_dwordx4 v[178:181], v191, s[58:59] offset:2048
	global_load_dwordx4 v[166:169], v192, s[58:59]
	global_load_dwordx4 v[182:185], v192, s[58:59] offset:2048
	global_load_dwordx4 v[170:173], v193, s[58:59]
	global_load_dwordx4 v[186:189], v193, s[58:59] offset:2048
	global_load_dwordx4 v[212:215], v194, s[60:61]
	global_load_dwordx4 v[216:219], v195, s[58:59]
	global_load_dwordx4 v[220:223], v195, s[58:59] offset:64
	global_load_dwordx4 v[224:227], v198, s[62:63]
	global_load_dwordx4 v[228:231], v199, s[62:63]
	s_waitcnt lgkmcnt(0)
	s_barrier
	s_waitcnt vmcnt(39)
	ds_write_b128 v200, v[2:5] offset:0
	ds_write_b128 v201, v[18:21] offset:17408
	ds_write_b128 v200, v[6:9] offset:4352
	ds_write_b128 v201, v[22:25] offset:22016
	ds_write_b128 v200, v[10:13] offset:8704
	ds_write_b128 v201, v[26:29] offset:26624
	ds_write_b128 v200, v[14:17] offset:13056
	ds_write_b128 v201, v[30:33] offset:31232
	ds_write_b128 v207, v[38:41] offset:36352
	ds_write_b128 v207, v[42:45] offset:37376
	ds_write_b128 v208, v[46:49] offset:44544
	ds_write_b128 v208, v[50:53] offset:45568
	s_cmp_eq_u32 s65, 0
	s_cbranch_scc1 .Lh2l_nodec_u3
	s_mov_b32 exec_hi, 0
	ds_write_b128 v206, v[34:37] offset:35840
	s_mov_b32 exec_hi, -1
.Lh2l_nodec_u3:
	s_add_u32 s56, s64, 8
	s_min_u32 s56, s56, 63
	s_lshl_b32 s57, s56, 19
	s_add_u32 s58, s44, s57
	s_addc_u32 s59, s45, 0
	s_lshl_b32 s57, s56, 9
	s_add_u32 s60, s46, s57
	s_addc_u32 s61, s47, 0
	s_lshl_b32 s57, s56, 14
	s_add_u32 s62, s48, s57
	s_addc_u32 s63, s49, 0
	global_load_dwordx4 v[2:5], v190, s[58:59]
	global_load_dwordx4 v[18:21], v190, s[58:59] offset:2048
	global_load_dwordx4 v[6:9], v191, s[58:59]
	global_load_dwordx4 v[22:25], v191, s[58:59] offset:2048
	global_load_dwordx4 v[10:13], v192, s[58:59]
	global_load_dwordx4 v[26:29], v192, s[58:59] offset:2048
	global_load_dwordx4 v[14:17], v193, s[58:59]
	global_load_dwordx4 v[30:33], v193, s[58:59] offset:2048
	global_load_dwordx4 v[34:37], v194, s[60:61]
	global_load_dwordx4 v[38:41], v195, s[58:59]
	global_load_dwordx4 v[42:45], v195, s[58:59] offset:64
	global_load_dwordx4 v[46:49], v198, s[62:63]
	global_load_dwordx4 v[50:53], v199, s[62:63]
	s_waitcnt lgkmcnt(0)
	s_barrier
	s_add_u32 s64, s64, 4
	s_cmp_lt_u32 s64, 64
	s_cbranch_scc1 .Lh2l_loop
